# k32: k28 + drop 15 vestigial s_waitcnt lgkmcnt(0) after masked ds_write in fused-residual epilogue first pass (no LDS result pending since permlane conversion; covering wait before barrier kept)
# baseline (speedup 1.0000x reference)
.LBB0_337:
	s_and_b64 vcc, exec, s[0:1]
	s_cbranch_vccz .LBB0_420
	s_lshl_b32 s100, s55, 8
	v_add_u32_e32 v218, s100, v147
	v_ashrrev_i32_e32 v219, 31, v218
	v_lshlrev_b64 v[218:219], 11, v[218:219]
	v_lshl_or_b32 v172, s10, 8, v156
	v_ashrrev_i32_e32 v173, 31, v172
	v_lshl_add_u64 v[218:219], s[4:5], 0, v[218:219]
	v_lshl_add_u64 v[218:219], v[172:173], 1, v[218:219]
	v_lshl_add_u64 v[172:173], v[172:173], 2, s[72:73]
	global_load_dwordx4 v[186:189], v[172:173], off
	global_load_dwordx4 v[190:193], v[172:173], off offset:16
	global_load_dwordx4 v[194:197], v[172:173], off offset:512
	global_load_dwordx4 v[198:201], v[172:173], off offset:528
	global_load_dwordx4 v[202:205], v[218:219], off
	global_load_dwordx4 v[206:209], v[218:219], off offset:256
	s_mov_b32 s100, 0x8000
	s_mov_b32 s101, 0
	v_lshl_add_u64 v[172:173], v[218:219], 0, s[100:101]
	global_load_dwordx4 v[210:213], v[172:173], off
	global_load_dwordx4 v[214:217], v[172:173], off offset:256
	v_lshl_add_u64 v[172:173], v[172:173], 0, s[100:101]
	global_load_dwordx4 v[232:235], v[172:173], off
	global_load_dwordx4 v[246:249], v[172:173], off offset:256
	v_pk_mul_f32 v[128:129], v[126:127], v[126:127]
	v_pk_mul_f32 v[130:131], v[124:125], v[124:125]
	v_pk_fma_f32 v[128:129], v[122:123], v[122:123], v[128:129]
	v_pk_fma_f32 v[130:131], v[120:121], v[120:121], v[130:131]
	v_pk_fma_f32 v[128:129], v[118:119], v[118:119], v[128:129]
	v_pk_fma_f32 v[130:131], v[116:117], v[116:117], v[130:131]
	v_pk_fma_f32 v[128:129], v[114:115], v[114:115], v[128:129]
	v_pk_fma_f32 v[130:131], v[112:113], v[112:113], v[130:131]
	v_add_f32_e32 v128, v128, v129
	v_add_f32_e32 v130, v130, v131
	v_add_f32_e32 v128, v130, v128
	v_mov_b32_e32 v129, v128
	s_nop 1
	v_permlane16_swap_b32_e32 v128, v129
	v_add_f32_e32 v128, v128, v129
	v_mov_b32_e32 v129, v128
	s_nop 1
	v_permlane32_swap_b32_e32 v128, v129
	s_and_saveexec_b64 s[0:1], s[38:39]
	s_cbranch_execz .LBB0_340
	v_add_f32_e32 v128, v128, v129
	ds_write_b32 v244, v128 offset:1024
.LBB0_340:
	s_or_b64 exec, exec, s[0:1]
	v_pk_mul_f32 v[128:129], v[110:111], v[110:111]
	v_pk_mul_f32 v[130:131], v[108:109], v[108:109]
	v_pk_fma_f32 v[128:129], v[106:107], v[106:107], v[128:129]
	v_pk_fma_f32 v[130:131], v[104:105], v[104:105], v[130:131]
	v_pk_fma_f32 v[128:129], v[102:103], v[102:103], v[128:129]
	v_pk_fma_f32 v[130:131], v[100:101], v[100:101], v[130:131]
	v_pk_fma_f32 v[128:129], v[98:99], v[98:99], v[128:129]
	v_pk_fma_f32 v[130:131], v[96:97], v[96:97], v[130:131]
	v_add_f32_e32 v128, v128, v129
	v_add_f32_e32 v130, v130, v131
	v_add_f32_e32 v128, v130, v128
	v_mov_b32_e32 v129, v128
	s_nop 1
	v_permlane16_swap_b32_e32 v128, v129
	v_add_f32_e32 v128, v128, v129
	v_mov_b32_e32 v129, v128
	s_nop 1
	v_permlane32_swap_b32_e32 v128, v129
	s_and_saveexec_b64 s[0:1], s[38:39]
	s_cbranch_execz .LBB0_342
	v_add_f32_e32 v128, v128, v129
	ds_write_b32 v244, v128 offset:1280
.LBB0_342:
	s_or_b64 exec, exec, s[0:1]
	v_pk_mul_f32 v[128:129], v[94:95], v[94:95]
	v_pk_mul_f32 v[130:131], v[92:93], v[92:93]
	v_pk_fma_f32 v[128:129], v[90:91], v[90:91], v[128:129]
	v_pk_fma_f32 v[130:131], v[88:89], v[88:89], v[130:131]
	v_pk_fma_f32 v[128:129], v[86:87], v[86:87], v[128:129]
	v_pk_fma_f32 v[130:131], v[84:85], v[84:85], v[130:131]
	v_pk_fma_f32 v[128:129], v[82:83], v[82:83], v[128:129]
	v_pk_fma_f32 v[130:131], v[80:81], v[80:81], v[130:131]
	v_add_f32_e32 v128, v128, v129
	v_add_f32_e32 v130, v130, v131
	v_add_f32_e32 v128, v130, v128
	v_mov_b32_e32 v129, v128
	s_nop 1
	v_permlane16_swap_b32_e32 v128, v129
	v_add_f32_e32 v128, v128, v129
	v_mov_b32_e32 v129, v128
	s_nop 1
	v_permlane32_swap_b32_e32 v128, v129
	s_and_saveexec_b64 s[0:1], s[38:39]
	s_cbranch_execz .LBB0_344
	v_add_f32_e32 v128, v128, v129
	ds_write_b32 v244, v128 offset:1536
.LBB0_344:
	s_or_b64 exec, exec, s[0:1]
	v_pk_mul_f32 v[128:129], v[78:79], v[78:79]
	v_pk_mul_f32 v[130:131], v[76:77], v[76:77]
	v_pk_fma_f32 v[128:129], v[74:75], v[74:75], v[128:129]
	v_pk_fma_f32 v[130:131], v[72:73], v[72:73], v[130:131]
	v_pk_fma_f32 v[128:129], v[70:71], v[70:71], v[128:129]
	v_pk_fma_f32 v[130:131], v[68:69], v[68:69], v[130:131]
	v_pk_fma_f32 v[128:129], v[66:67], v[66:67], v[128:129]
	v_pk_fma_f32 v[130:131], v[64:65], v[64:65], v[130:131]
	v_add_f32_e32 v128, v128, v129
	v_add_f32_e32 v130, v130, v131
	v_add_f32_e32 v128, v130, v128
	v_mov_b32_e32 v129, v128
	s_nop 1
	v_permlane16_swap_b32_e32 v128, v129
	v_add_f32_e32 v128, v128, v129
	v_mov_b32_e32 v129, v128
	s_nop 1
	v_permlane32_swap_b32_e32 v128, v129
	s_and_saveexec_b64 s[0:1], s[38:39]
	s_cbranch_execz .LBB0_346
	v_add_f32_e32 v128, v128, v129
	ds_write_b32 v244, v128 offset:1792
.LBB0_346:
	s_or_b64 exec, exec, s[0:1]
	v_pk_mul_f32 v[128:129], v[62:63], v[62:63]
	v_pk_mul_f32 v[130:131], v[60:61], v[60:61]
	v_pk_fma_f32 v[128:129], v[58:59], v[58:59], v[128:129]
	v_pk_fma_f32 v[130:131], v[56:57], v[56:57], v[130:131]
	v_pk_fma_f32 v[128:129], v[54:55], v[54:55], v[128:129]
	v_pk_fma_f32 v[130:131], v[52:53], v[52:53], v[130:131]
	v_pk_fma_f32 v[128:129], v[50:51], v[50:51], v[128:129]
	v_pk_fma_f32 v[130:131], v[48:49], v[48:49], v[130:131]
	v_add_f32_e32 v128, v128, v129
	v_add_f32_e32 v130, v130, v131
	v_add_f32_e32 v128, v130, v128
	v_mov_b32_e32 v129, v128
	s_nop 1
	v_permlane16_swap_b32_e32 v128, v129
	v_add_f32_e32 v128, v128, v129
	v_mov_b32_e32 v129, v128
	s_nop 1
	v_permlane32_swap_b32_e32 v128, v129
	s_and_saveexec_b64 s[0:1], s[38:39]
	s_cbranch_execz .LBB0_348
	v_add_f32_e32 v128, v128, v129
	ds_write_b32 v244, v128 offset:3072
.LBB0_348:
	s_or_b64 exec, exec, s[0:1]
	v_pk_mul_f32 v[128:129], v[46:47], v[46:47]
	v_pk_mul_f32 v[130:131], v[44:45], v[44:45]
	v_pk_fma_f32 v[128:129], v[42:43], v[42:43], v[128:129]
	v_pk_fma_f32 v[130:131], v[40:41], v[40:41], v[130:131]
	v_pk_fma_f32 v[128:129], v[38:39], v[38:39], v[128:129]
	v_pk_fma_f32 v[130:131], v[36:37], v[36:37], v[130:131]
	v_pk_fma_f32 v[128:129], v[34:35], v[34:35], v[128:129]
	v_pk_fma_f32 v[130:131], v[32:33], v[32:33], v[130:131]
	v_add_f32_e32 v128, v128, v129
	v_add_f32_e32 v130, v130, v131
	v_add_f32_e32 v128, v130, v128
	v_mov_b32_e32 v129, v128
	s_nop 1
	v_permlane16_swap_b32_e32 v128, v129
	v_add_f32_e32 v128, v128, v129
	v_mov_b32_e32 v129, v128
	s_nop 1
	v_permlane32_swap_b32_e32 v128, v129
	s_and_saveexec_b64 s[0:1], s[38:39]
	s_cbranch_execz .LBB0_350
	v_add_f32_e32 v128, v128, v129
	ds_write_b32 v244, v128 offset:3328
.LBB0_350:
	s_or_b64 exec, exec, s[0:1]
	v_pk_mul_f32 v[128:129], v[30:31], v[30:31]
	v_pk_mul_f32 v[130:131], v[28:29], v[28:29]
	v_pk_fma_f32 v[128:129], v[26:27], v[26:27], v[128:129]
	v_pk_fma_f32 v[130:131], v[24:25], v[24:25], v[130:131]
	v_pk_fma_f32 v[128:129], v[22:23], v[22:23], v[128:129]
	v_pk_fma_f32 v[130:131], v[20:21], v[20:21], v[130:131]
	v_pk_fma_f32 v[128:129], v[18:19], v[18:19], v[128:129]
	v_pk_fma_f32 v[130:131], v[16:17], v[16:17], v[130:131]
	v_add_f32_e32 v128, v128, v129
	v_add_f32_e32 v130, v130, v131
	v_add_f32_e32 v128, v130, v128
	v_mov_b32_e32 v129, v128
	s_nop 1
	v_permlane16_swap_b32_e32 v128, v129
	v_add_f32_e32 v128, v128, v129
	v_mov_b32_e32 v129, v128
	s_nop 1
	v_permlane32_swap_b32_e32 v128, v129
	s_and_saveexec_b64 s[0:1], s[38:39]
	s_cbranch_execz .LBB0_352
	v_add_f32_e32 v128, v128, v129
	ds_write_b32 v244, v128 offset:3584
.LBB0_352:
	s_or_b64 exec, exec, s[0:1]
	v_pk_mul_f32 v[128:129], v[14:15], v[14:15]
	v_pk_mul_f32 v[130:131], v[12:13], v[12:13]
	v_pk_fma_f32 v[128:129], v[10:11], v[10:11], v[128:129]
	v_pk_fma_f32 v[130:131], v[8:9], v[8:9], v[130:131]
	v_pk_fma_f32 v[128:129], v[6:7], v[6:7], v[128:129]
	v_pk_fma_f32 v[130:131], v[4:5], v[4:5], v[130:131]
	v_pk_fma_f32 v[128:129], v[2:3], v[2:3], v[128:129]
	v_pk_fma_f32 v[130:131], v[0:1], v[0:1], v[130:131]
	v_add_f32_e32 v128, v128, v129
	v_add_f32_e32 v130, v130, v131
	v_add_f32_e32 v128, v130, v128
	v_mov_b32_e32 v129, v128
	s_nop 1
	v_permlane16_swap_b32_e32 v128, v129
	v_add_f32_e32 v128, v128, v129
	v_mov_b32_e32 v129, v128
	s_nop 1
	v_permlane32_swap_b32_e32 v128, v129
	s_and_saveexec_b64 s[0:1], s[38:39]
	s_cbranch_execz .LBB0_354
	v_add_f32_e32 v128, v128, v129
	ds_write_b32 v244, v128 offset:3840
